# SSD chunk loop: row partial-sum xor-16/32 reduction via v_permlane16/32_swap instead of two ds_bpermute round trips (plus the DPP decay scan)
# baseline (speedup 1.0000x reference)
; __device__ __forceinline__ u32x2 pack4(f32x4 v) { u32x2 r; r.x = cvt_pk(v[0], v[1]); r.y = cvt_pk(v[2], v[3]); return r; }
; __device__ __forceinline__ float bf2f(u16 h) { return __uint_as_float(((unsigned)h) << 16); }
; __device__ __forceinline__ f32x4 unpack4(u32x2 w) { return (f32x4){bflo(w.x), bfhi(w.x), bflo(w.y), bfhi(w.y)}; }
; __device__ __forceinline__ float shfl_xor_f(float v, int mask) { const int l = lane_fresh(); return __int_as_float(__builtin_amdgcn_ds_bpermute((l ^ mask) << 2, __float_as_int(v))); }
; __device__ __forceinline__ void ssd_prompt_item(const Params& p, int item, const int wv) {
;     ...
;         const int pc = pb * 16 + fq * 4;
;         f32x4 zs = unpack4(zsr[pb]);
; #pragma unroll
;         for (int e = 0; e < 4; ++e) { float xv = bf2f(xT_l[(pc + e) * 136 + i]); y[e] = (y[e] + xv * Dh) * zs[e]; ss += y[e] * y[e]; }
;         ypk[pb] = pack4(y);
;       }
;       store_pair16(Y + (size_t)tok * 1024 + h * 64, ypk[0], ypk[1], fq);
;       store_pair16(Y + (size_t)tok * 1024 + h * 64 + 32, ypk[2], ypk[3], fq);
;       ss += shfl_xor_f(ss, 16); ss += shfl_xor_f(ss, 32);
;       if (fq == 0) { YPS[(size_t)tok * 32 + g * 16 + (h & 7) * 2] = ss; YPS[(size_t)tok * 32 + g * 16 + (h & 7) * 2 + 1] = 0.f; }
.LBB0_623:
	v_lshlrev_b32_e32 v87, 16, v129
	v_lshlrev_b32_e32 v86, 16, v128
	s_waitcnt vmcnt(3)
	v_lshlrev_b32_e32 v84, 16, v138
	v_and_b32_e32 v85, 0xffff0000, v138
	v_pk_fma_f32 v[86:87], v[144:145], v[86:87], v[100:101]
	v_lshlrev_b32_e32 v89, 16, v127
	v_lshlrev_b32_e32 v88, 16, v126
	v_pk_mul_f32 v[86:87], v[86:87], v[84:85]
	v_lshlrev_b32_e32 v84, 16, v139
	v_and_b32_e32 v85, 0xffff0000, v139
	v_pk_fma_f32 v[88:89], v[144:145], v[88:89], v[102:103]
	v_lshlrev_b32_e32 v91, 16, v131
	v_pk_mul_f32 v[94:95], v[88:89], v[84:85]
	v_lshlrev_b32_e32 v89, 16, v141
	v_lshlrev_b32_e32 v88, 16, v140
	s_waitcnt vmcnt(2)
	v_lshlrev_b32_e32 v84, 16, v136
	v_and_b32_e32 v85, 0xffff0000, v136
	v_pk_fma_f32 v[88:89], v[144:145], v[88:89], v[116:117]
	v_lshlrev_b32_e32 v90, 16, v130
	v_pk_mul_f32 v[88:89], v[88:89], v[84:85]
	v_lshlrev_b32_e32 v84, 16, v137
	v_and_b32_e32 v85, 0xffff0000, v137
	v_pk_fma_f32 v[90:91], v[144:145], v[90:91], v[118:119]
	v_pk_mul_f32 v[92:93], v[86:87], v[86:87]
	v_pk_mul_f32 v[100:101], v[90:91], v[84:85]
	v_lshlrev_b32_e32 v91, 16, v228
	v_lshlrev_b32_e32 v90, 16, v191
	s_waitcnt vmcnt(1)
	v_lshlrev_b32_e32 v84, 16, v134
	v_and_b32_e32 v85, 0xffff0000, v134
	v_pk_fma_f32 v[90:91], v[144:145], v[90:91], v[120:121]
	v_lshlrev_b32_e32 v107, 16, v190
	v_lshlrev_b32_e32 v106, 16, v142
	v_pk_mul_f32 v[96:97], v[94:95], v[94:95]
	v_pk_mul_f32 v[84:85], v[90:91], v[84:85]
	v_lshlrev_b32_e32 v90, 16, v135
	v_and_b32_e32 v91, 0xffff0000, v135
	v_pk_fma_f32 v[106:107], v[144:145], v[106:107], v[122:123]
	v_add_f32_e32 v92, v92, v93
	v_pk_mul_f32 v[90:91], v[106:107], v[90:91]
	v_add_f32_e32 v92, v92, v96
	v_pk_mul_f32 v[98:99], v[88:89], v[88:89]
	v_pk_mul_f32 v[104:105], v[84:85], v[84:85]
	v_pk_mul_f32 v[106:107], v[90:91], v[90:91]
	v_cvt_pk_bf16_f32 v84, v84, v85
	v_cvt_pk_bf16_f32 v85, v90, v91
	v_cvt_pk_bf16_f32 v90, v88, v89
	v_cvt_pk_bf16_f32 v89, v94, v95
	ds_read_u16 v94, v226 offset:13056
	ds_read_u16 v95, v226 offset:13328
	v_add_f32_e32 v92, v92, v97
	v_add_f32_e32 v92, v92, v98
	v_pk_mul_f32 v[102:103], v[100:101], v[100:101]
	v_cvt_pk_bf16_f32 v91, v100, v101
	ds_read_u16 v100, v226 offset:13600
	ds_read_u16 v101, v226 offset:13872
	v_add_f32_e32 v92, v92, v99
	v_add_f32_e32 v92, v92, v102
	v_add_f32_e32 v92, v92, v103
	s_waitcnt lgkmcnt(2)
	v_lshlrev_b32_e32 v95, 16, v95
	v_lshlrev_b32_e32 v94, 16, v94
	v_add_f32_e32 v92, v92, v104
	v_cvt_pk_bf16_f32 v88, v86, v87
	s_waitcnt vmcnt(0)
	v_lshlrev_b32_e32 v86, 16, v132
	v_and_b32_e32 v87, 0xffff0000, v132
	v_pk_fma_f32 v[80:81], v[144:145], v[94:95], v[80:81]
	v_add_f32_e32 v92, v92, v105
	v_pk_mul_f32 v[80:81], v[80:81], v[86:87]
	s_waitcnt lgkmcnt(0)
	v_lshlrev_b32_e32 v101, 16, v101
	v_lshlrev_b32_e32 v100, 16, v100
	v_add_f32_e32 v92, v92, v106
	v_pk_mul_f32 v[86:87], v[80:81], v[80:81]
	v_lshlrev_b32_e32 v94, 16, v133
	v_and_b32_e32 v95, 0xffff0000, v133
	v_pk_fma_f32 v[82:83], v[144:145], v[100:101], v[82:83]
	v_add_f32_e32 v92, v92, v107
	v_pk_mul_f32 v[82:83], v[82:83], v[94:95]
	v_add_f32_e32 v86, v92, v86
	v_pk_mul_f32 v[94:95], v[82:83], v[82:83]
	v_add_f32_e32 v86, v86, v87
	v_add_f32_e32 v86, v86, v94
	v_add_f32_e32 v92, v86, v95
	v_cvt_pk_bf16_f32 v86, v80, v81
	v_cvt_pk_bf16_f32 v87, v82, v83
	v_permlane16_swap_b32_e32 v88, v90
	v_permlane16_swap_b32_e32 v89, v91
	v_permlane16_swap_b32_e32 v84, v86
	v_permlane16_swap_b32_e32 v85, v87
	global_store_dwordx4 v[188:189], v[88:91], off offset:-64
	global_store_dwordx4 v[188:189], v[84:87], off
	v_mov_b32_e32 v80, v92
	v_mov_b32_e32 v81, v92
	s_nop 1
	v_permlane16_swap_b32_e32 v80, v81
	v_add_f32_e32 v80, v80, v81
	v_mov_b32_e32 v81, v80
	s_nop 1
	v_permlane32_swap_b32_e32 v80, v81
	s_and_saveexec_b64 s[84:85], s[4:5]
	s_cbranch_execz .LBB0_569
	s_waitcnt lgkmcnt(0)
	v_add_f32_e32 v142, v80, v81
	v_lshl_add_u64 v[80:81], s[50:51], 0, v[184:185]
	v_add_co_u32_e32 v80, vcc, 0x2f22000, v80
	s_nop 1
	v_addc_co_u32_e32 v81, vcc, 0, v81, vcc
	global_store_dwordx2 v[80:81], v[142:143], off
	s_branch .LBB0_569
